# plus gate_gemm K-loop 32-deep load pipeline; NVT transposed stores via quad DPP transpose + dwordx2
# speedup vs baseline: 1.0076x; 1.0019x over previous
.LBB0_500:
	s_andn2_b64 vcc, exec, s[6:7]
	s_cbranch_vccnz .LBB0_502
	s_ashr_i32 s6, s21, 4
	v_lshl_add_u32 v157, s19, 8, v188
	s_and_b32 s6, s6, 0xfffffe00
	v_or_b32_e32 v130, s6, v157
	v_ashrrev_i32_e32 v131, 31, v130
	v_and_b32_e32 v134, 0x1fcf, v156
	v_lshlrev_b64 v[132:133], 14, v[130:131]
	v_lshl_add_u64 v[132:133], s[10:11], 0, v[132:133]
	v_lshlrev_b32_e32 v176, 1, v134
	v_lshl_add_u64 v[132:133], v[132:133], 0, v[176:177]
	s_waitcnt lgkmcnt(0)
	v_mbcnt_lo_u32_b32 v157, -1, 0
	v_mbcnt_hi_u32_b32 v157, -1, v157
	s_mov_b32 s6, 0xcccccccc
	s_mov_b32 s7, 0xcccccccc
	v_and_b32_e32 v159, 3, v157
	v_and_b32_e32 v170, 1, v157
	v_mul_u32_u24_e32 v159, 0x3ffe, v159
	v_mov_b32_e32 v171, 0x5040100
	v_mov_b32_e32 v172, 0x3020706
	v_cmp_eq_u32_e32 vcc, 1, v170
	v_cndmask_b32_e32 v171, v171, v172, vcc
	v_add_co_u32_e32 v132, vcc, v132, v159
	v_addc_co_u32_e32 v133, vcc, 0, v133, vcc
	v_add_co_u32_e32 v134, vcc, 0x40000, v132
	v_addc_co_u32_e32 v135, vcc, 0, v133, vcc
	v_add_co_u32_e32 v136, vcc, 0x200000, v132
	v_addc_co_u32_e32 v137, vcc, 0, v133, vcc
	v_add_co_u32_e32 v138, vcc, 0x240000, v132
	v_addc_co_u32_e32 v139, vcc, 0, v133, vcc
	v_pk_mul_f32 v[140:141], v[124:125], v[168:169] op_sel_hi:[1,0]
	v_pk_mul_f32 v[142:143], v[126:127], v[168:169] op_sel_hi:[1,0]
	v_pk_mul_f32 v[200:201], v[120:121], v[168:169] op_sel_hi:[1,0]
	v_pk_mul_f32 v[202:203], v[122:123], v[168:169] op_sel_hi:[1,0]
	v_cvt_pk_bf16_f32 v190, v140, v141
	v_cvt_pk_bf16_f32 v191, v142, v143
	v_cvt_pk_bf16_f32 v204, v200, v201
	v_cvt_pk_bf16_f32 v205, v202, v203
	v_mov_b32_dpp v192, v190 quad_perm:[1,0,3,2] row_mask:0xf bank_mask:0xf
	v_mov_b32_dpp v193, v191 quad_perm:[1,0,3,2] row_mask:0xf bank_mask:0xf
	v_mov_b32_dpp v206, v204 quad_perm:[1,0,3,2] row_mask:0xf bank_mask:0xf
	v_mov_b32_dpp v207, v205 quad_perm:[1,0,3,2] row_mask:0xf bank_mask:0xf
	v_perm_b32 v194, v192, v190, v171
	v_perm_b32 v195, v193, v191, v171
	v_perm_b32 v130, v206, v204, v171
	v_perm_b32 v131, v207, v205, v171
	v_mov_b32_dpp v196, v194 quad_perm:[2,3,0,1] row_mask:0xf bank_mask:0xf
	v_mov_b32_dpp v197, v195 quad_perm:[2,3,0,1] row_mask:0xf bank_mask:0xf
	v_mov_b32_dpp v172, v130 quad_perm:[2,3,0,1] row_mask:0xf bank_mask:0xf
	v_mov_b32_dpp v173, v131 quad_perm:[2,3,0,1] row_mask:0xf bank_mask:0xf
	v_cndmask_b32_e64 v198, v194, v197, s[6:7]
	v_cndmask_b32_e64 v199, v196, v195, s[6:7]
	v_cndmask_b32_e64 v200, v130, v173, s[6:7]
	v_cndmask_b32_e64 v201, v172, v131, s[6:7]
	global_store_dwordx2 v[132:133], v[198:199], off
	global_store_dwordx2 v[134:135], v[200:201], off
	v_pk_mul_f32 v[140:141], v[116:117], v[168:169] op_sel_hi:[1,0]
	v_pk_mul_f32 v[142:143], v[118:119], v[168:169] op_sel_hi:[1,0]
	v_pk_mul_f32 v[200:201], v[112:113], v[168:169] op_sel_hi:[1,0]
	v_pk_mul_f32 v[202:203], v[114:115], v[168:169] op_sel_hi:[1,0]
	v_cvt_pk_bf16_f32 v190, v140, v141
	v_cvt_pk_bf16_f32 v191, v142, v143
	v_cvt_pk_bf16_f32 v204, v200, v201
	v_cvt_pk_bf16_f32 v205, v202, v203
	v_mov_b32_dpp v192, v190 quad_perm:[1,0,3,2] row_mask:0xf bank_mask:0xf
	v_mov_b32_dpp v193, v191 quad_perm:[1,0,3,2] row_mask:0xf bank_mask:0xf
	v_mov_b32_dpp v206, v204 quad_perm:[1,0,3,2] row_mask:0xf bank_mask:0xf
	v_mov_b32_dpp v207, v205 quad_perm:[1,0,3,2] row_mask:0xf bank_mask:0xf
	v_perm_b32 v194, v192, v190, v171
	v_perm_b32 v195, v193, v191, v171
	v_perm_b32 v130, v206, v204, v171
	v_perm_b32 v131, v207, v205, v171
	v_mov_b32_dpp v196, v194 quad_perm:[2,3,0,1] row_mask:0xf bank_mask:0xf
	v_mov_b32_dpp v197, v195 quad_perm:[2,3,0,1] row_mask:0xf bank_mask:0xf
	v_mov_b32_dpp v172, v130 quad_perm:[2,3,0,1] row_mask:0xf bank_mask:0xf
	v_mov_b32_dpp v173, v131 quad_perm:[2,3,0,1] row_mask:0xf bank_mask:0xf
	v_cndmask_b32_e64 v198, v194, v197, s[6:7]
	v_cndmask_b32_e64 v199, v196, v195, s[6:7]
	v_cndmask_b32_e64 v200, v130, v173, s[6:7]
	v_cndmask_b32_e64 v201, v172, v131, s[6:7]
	global_store_dwordx2 v[136:137], v[198:199], off
	global_store_dwordx2 v[138:139], v[200:201], off
	v_pk_mul_f32 v[140:141], v[108:109], v[168:169] op_sel:[0,1]
	v_pk_mul_f32 v[142:143], v[110:111], v[168:169] op_sel:[0,1]
	v_pk_mul_f32 v[200:201], v[104:105], v[168:169] op_sel:[0,1]
	v_pk_mul_f32 v[202:203], v[106:107], v[168:169] op_sel:[0,1]
	v_cvt_pk_bf16_f32 v190, v140, v141
	v_cvt_pk_bf16_f32 v191, v142, v143
	v_cvt_pk_bf16_f32 v204, v200, v201
	v_cvt_pk_bf16_f32 v205, v202, v203
	v_mov_b32_dpp v192, v190 quad_perm:[1,0,3,2] row_mask:0xf bank_mask:0xf
	v_mov_b32_dpp v193, v191 quad_perm:[1,0,3,2] row_mask:0xf bank_mask:0xf
	v_mov_b32_dpp v206, v204 quad_perm:[1,0,3,2] row_mask:0xf bank_mask:0xf
	v_mov_b32_dpp v207, v205 quad_perm:[1,0,3,2] row_mask:0xf bank_mask:0xf
	v_perm_b32 v194, v192, v190, v171
	v_perm_b32 v195, v193, v191, v171
	v_perm_b32 v130, v206, v204, v171
	v_perm_b32 v131, v207, v205, v171
	v_mov_b32_dpp v196, v194 quad_perm:[2,3,0,1] row_mask:0xf bank_mask:0xf
	v_mov_b32_dpp v197, v195 quad_perm:[2,3,0,1] row_mask:0xf bank_mask:0xf
	v_mov_b32_dpp v172, v130 quad_perm:[2,3,0,1] row_mask:0xf bank_mask:0xf
	v_mov_b32_dpp v173, v131 quad_perm:[2,3,0,1] row_mask:0xf bank_mask:0xf
	v_cndmask_b32_e64 v198, v194, v197, s[6:7]
	v_cndmask_b32_e64 v199, v196, v195, s[6:7]
	v_cndmask_b32_e64 v200, v130, v173, s[6:7]
	v_cndmask_b32_e64 v201, v172, v131, s[6:7]
	global_store_dwordx2 v[132:133], v[198:199], off offset:32
	global_store_dwordx2 v[134:135], v[200:201], off offset:32
	v_pk_mul_f32 v[140:141], v[100:101], v[168:169] op_sel:[0,1]
	v_pk_mul_f32 v[142:143], v[102:103], v[168:169] op_sel:[0,1]
	v_pk_mul_f32 v[200:201], v[96:97], v[168:169] op_sel:[0,1]
	v_pk_mul_f32 v[202:203], v[98:99], v[168:169] op_sel:[0,1]
	v_cvt_pk_bf16_f32 v190, v140, v141
	v_cvt_pk_bf16_f32 v191, v142, v143
	v_cvt_pk_bf16_f32 v204, v200, v201
	v_cvt_pk_bf16_f32 v205, v202, v203
	v_mov_b32_dpp v192, v190 quad_perm:[1,0,3,2] row_mask:0xf bank_mask:0xf
	v_mov_b32_dpp v193, v191 quad_perm:[1,0,3,2] row_mask:0xf bank_mask:0xf
	v_mov_b32_dpp v206, v204 quad_perm:[1,0,3,2] row_mask:0xf bank_mask:0xf
	v_mov_b32_dpp v207, v205 quad_perm:[1,0,3,2] row_mask:0xf bank_mask:0xf
	v_perm_b32 v194, v192, v190, v171
	v_perm_b32 v195, v193, v191, v171
	v_perm_b32 v130, v206, v204, v171
	v_perm_b32 v131, v207, v205, v171
	v_mov_b32_dpp v196, v194 quad_perm:[2,3,0,1] row_mask:0xf bank_mask:0xf
	v_mov_b32_dpp v197, v195 quad_perm:[2,3,0,1] row_mask:0xf bank_mask:0xf
	v_mov_b32_dpp v172, v130 quad_perm:[2,3,0,1] row_mask:0xf bank_mask:0xf
	v_mov_b32_dpp v173, v131 quad_perm:[2,3,0,1] row_mask:0xf bank_mask:0xf
	v_cndmask_b32_e64 v198, v194, v197, s[6:7]
	v_cndmask_b32_e64 v199, v196, v195, s[6:7]
	v_cndmask_b32_e64 v200, v130, v173, s[6:7]
	v_cndmask_b32_e64 v201, v172, v131, s[6:7]
	global_store_dwordx2 v[136:137], v[198:199], off offset:32
	global_store_dwordx2 v[138:139], v[200:201], off offset:32
	v_pk_mul_f32 v[140:141], v[92:93], v[166:167] op_sel_hi:[1,0]
	v_pk_mul_f32 v[142:143], v[94:95], v[166:167] op_sel_hi:[1,0]
	v_pk_mul_f32 v[200:201], v[88:89], v[166:167] op_sel_hi:[1,0]
	v_pk_mul_f32 v[202:203], v[90:91], v[166:167] op_sel_hi:[1,0]
	v_cvt_pk_bf16_f32 v190, v140, v141
	v_cvt_pk_bf16_f32 v191, v142, v143
	v_cvt_pk_bf16_f32 v204, v200, v201
	v_cvt_pk_bf16_f32 v205, v202, v203
	v_mov_b32_dpp v192, v190 quad_perm:[1,0,3,2] row_mask:0xf bank_mask:0xf
	v_mov_b32_dpp v193, v191 quad_perm:[1,0,3,2] row_mask:0xf bank_mask:0xf
	v_mov_b32_dpp v206, v204 quad_perm:[1,0,3,2] row_mask:0xf bank_mask:0xf
	v_mov_b32_dpp v207, v205 quad_perm:[1,0,3,2] row_mask:0xf bank_mask:0xf
	v_perm_b32 v194, v192, v190, v171
	v_perm_b32 v195, v193, v191, v171
	v_perm_b32 v130, v206, v204, v171
	v_perm_b32 v131, v207, v205, v171
	v_mov_b32_dpp v196, v194 quad_perm:[2,3,0,1] row_mask:0xf bank_mask:0xf
	v_mov_b32_dpp v197, v195 quad_perm:[2,3,0,1] row_mask:0xf bank_mask:0xf
	v_mov_b32_dpp v172, v130 quad_perm:[2,3,0,1] row_mask:0xf bank_mask:0xf
	v_mov_b32_dpp v173, v131 quad_perm:[2,3,0,1] row_mask:0xf bank_mask:0xf
	v_cndmask_b32_e64 v198, v194, v197, s[6:7]
	v_cndmask_b32_e64 v199, v196, v195, s[6:7]
	v_cndmask_b32_e64 v200, v130, v173, s[6:7]
	v_cndmask_b32_e64 v201, v172, v131, s[6:7]
	global_store_dwordx2 v[132:133], v[198:199], off offset:64
	global_store_dwordx2 v[134:135], v[200:201], off offset:64
	v_pk_mul_f32 v[140:141], v[84:85], v[166:167] op_sel_hi:[1,0]
	v_pk_mul_f32 v[142:143], v[86:87], v[166:167] op_sel_hi:[1,0]
	v_pk_mul_f32 v[200:201], v[80:81], v[166:167] op_sel_hi:[1,0]
	v_pk_mul_f32 v[202:203], v[82:83], v[166:167] op_sel_hi:[1,0]
	v_cvt_pk_bf16_f32 v190, v140, v141
	v_cvt_pk_bf16_f32 v191, v142, v143
	v_cvt_pk_bf16_f32 v204, v200, v201
	v_cvt_pk_bf16_f32 v205, v202, v203
	v_mov_b32_dpp v192, v190 quad_perm:[1,0,3,2] row_mask:0xf bank_mask:0xf
	v_mov_b32_dpp v193, v191 quad_perm:[1,0,3,2] row_mask:0xf bank_mask:0xf
	v_mov_b32_dpp v206, v204 quad_perm:[1,0,3,2] row_mask:0xf bank_mask:0xf
	v_mov_b32_dpp v207, v205 quad_perm:[1,0,3,2] row_mask:0xf bank_mask:0xf
	v_perm_b32 v194, v192, v190, v171
	v_perm_b32 v195, v193, v191, v171
	v_perm_b32 v130, v206, v204, v171
	v_perm_b32 v131, v207, v205, v171
	v_mov_b32_dpp v196, v194 quad_perm:[2,3,0,1] row_mask:0xf bank_mask:0xf
	v_mov_b32_dpp v197, v195 quad_perm:[2,3,0,1] row_mask:0xf bank_mask:0xf
	v_mov_b32_dpp v172, v130 quad_perm:[2,3,0,1] row_mask:0xf bank_mask:0xf
	v_mov_b32_dpp v173, v131 quad_perm:[2,3,0,1] row_mask:0xf bank_mask:0xf
	v_cndmask_b32_e64 v198, v194, v197, s[6:7]
	v_cndmask_b32_e64 v199, v196, v195, s[6:7]
	v_cndmask_b32_e64 v200, v130, v173, s[6:7]
	v_cndmask_b32_e64 v201, v172, v131, s[6:7]
	global_store_dwordx2 v[136:137], v[198:199], off offset:64
	global_store_dwordx2 v[138:139], v[200:201], off offset:64
	v_pk_mul_f32 v[140:141], v[76:77], v[166:167] op_sel:[0,1]
	v_pk_mul_f32 v[142:143], v[78:79], v[166:167] op_sel:[0,1]
	v_pk_mul_f32 v[200:201], v[72:73], v[166:167] op_sel:[0,1]
	v_pk_mul_f32 v[202:203], v[74:75], v[166:167] op_sel:[0,1]
	v_cvt_pk_bf16_f32 v190, v140, v141
	v_cvt_pk_bf16_f32 v191, v142, v143
	v_cvt_pk_bf16_f32 v204, v200, v201
	v_cvt_pk_bf16_f32 v205, v202, v203
	v_mov_b32_dpp v192, v190 quad_perm:[1,0,3,2] row_mask:0xf bank_mask:0xf
	v_mov_b32_dpp v193, v191 quad_perm:[1,0,3,2] row_mask:0xf bank_mask:0xf
	v_mov_b32_dpp v206, v204 quad_perm:[1,0,3,2] row_mask:0xf bank_mask:0xf
	v_mov_b32_dpp v207, v205 quad_perm:[1,0,3,2] row_mask:0xf bank_mask:0xf
	v_perm_b32 v194, v192, v190, v171
	v_perm_b32 v195, v193, v191, v171
	v_perm_b32 v130, v206, v204, v171
	v_perm_b32 v131, v207, v205, v171
	v_mov_b32_dpp v196, v194 quad_perm:[2,3,0,1] row_mask:0xf bank_mask:0xf
	v_mov_b32_dpp v197, v195 quad_perm:[2,3,0,1] row_mask:0xf bank_mask:0xf
	v_mov_b32_dpp v172, v130 quad_perm:[2,3,0,1] row_mask:0xf bank_mask:0xf
	v_mov_b32_dpp v173, v131 quad_perm:[2,3,0,1] row_mask:0xf bank_mask:0xf
	v_cndmask_b32_e64 v198, v194, v197, s[6:7]
	v_cndmask_b32_e64 v199, v196, v195, s[6:7]
	v_cndmask_b32_e64 v200, v130, v173, s[6:7]
	v_cndmask_b32_e64 v201, v172, v131, s[6:7]
	global_store_dwordx2 v[132:133], v[198:199], off offset:96
	global_store_dwordx2 v[134:135], v[200:201], off offset:96
	v_pk_mul_f32 v[140:141], v[68:69], v[166:167] op_sel:[0,1]
	v_pk_mul_f32 v[142:143], v[70:71], v[166:167] op_sel:[0,1]
	v_pk_mul_f32 v[200:201], v[64:65], v[166:167] op_sel:[0,1]
	v_pk_mul_f32 v[202:203], v[66:67], v[166:167] op_sel:[0,1]
	v_cvt_pk_bf16_f32 v190, v140, v141
	v_cvt_pk_bf16_f32 v191, v142, v143
	v_cvt_pk_bf16_f32 v204, v200, v201
	v_cvt_pk_bf16_f32 v205, v202, v203
	v_mov_b32_dpp v192, v190 quad_perm:[1,0,3,2] row_mask:0xf bank_mask:0xf
	v_mov_b32_dpp v193, v191 quad_perm:[1,0,3,2] row_mask:0xf bank_mask:0xf
	v_mov_b32_dpp v206, v204 quad_perm:[1,0,3,2] row_mask:0xf bank_mask:0xf
	v_mov_b32_dpp v207, v205 quad_perm:[1,0,3,2] row_mask:0xf bank_mask:0xf
	v_perm_b32 v194, v192, v190, v171
	v_perm_b32 v195, v193, v191, v171
	v_perm_b32 v130, v206, v204, v171
	v_perm_b32 v131, v207, v205, v171
	v_mov_b32_dpp v196, v194 quad_perm:[2,3,0,1] row_mask:0xf bank_mask:0xf
	v_mov_b32_dpp v197, v195 quad_perm:[2,3,0,1] row_mask:0xf bank_mask:0xf
	v_mov_b32_dpp v172, v130 quad_perm:[2,3,0,1] row_mask:0xf bank_mask:0xf
	v_mov_b32_dpp v173, v131 quad_perm:[2,3,0,1] row_mask:0xf bank_mask:0xf
	v_cndmask_b32_e64 v198, v194, v197, s[6:7]
	v_cndmask_b32_e64 v199, v196, v195, s[6:7]
	v_cndmask_b32_e64 v200, v130, v173, s[6:7]
	v_cndmask_b32_e64 v201, v172, v131, s[6:7]
	global_store_dwordx2 v[136:137], v[198:199], off offset:96
	global_store_dwordx2 v[138:139], v[200:201], off offset:96
	v_pk_mul_f32 v[140:141], v[60:61], v[162:163] op_sel_hi:[1,0]
	v_pk_mul_f32 v[142:143], v[62:63], v[162:163] op_sel_hi:[1,0]
	v_pk_mul_f32 v[200:201], v[56:57], v[162:163] op_sel_hi:[1,0]
	v_pk_mul_f32 v[202:203], v[58:59], v[162:163] op_sel_hi:[1,0]
	v_cvt_pk_bf16_f32 v190, v140, v141
	v_cvt_pk_bf16_f32 v191, v142, v143
	v_cvt_pk_bf16_f32 v204, v200, v201
	v_cvt_pk_bf16_f32 v205, v202, v203
	v_mov_b32_dpp v192, v190 quad_perm:[1,0,3,2] row_mask:0xf bank_mask:0xf
	v_mov_b32_dpp v193, v191 quad_perm:[1,0,3,2] row_mask:0xf bank_mask:0xf
	v_mov_b32_dpp v206, v204 quad_perm:[1,0,3,2] row_mask:0xf bank_mask:0xf
	v_mov_b32_dpp v207, v205 quad_perm:[1,0,3,2] row_mask:0xf bank_mask:0xf
	v_perm_b32 v194, v192, v190, v171
	v_perm_b32 v195, v193, v191, v171
	v_perm_b32 v130, v206, v204, v171
	v_perm_b32 v131, v207, v205, v171
	v_mov_b32_dpp v196, v194 quad_perm:[2,3,0,1] row_mask:0xf bank_mask:0xf
	v_mov_b32_dpp v197, v195 quad_perm:[2,3,0,1] row_mask:0xf bank_mask:0xf
	v_mov_b32_dpp v172, v130 quad_perm:[2,3,0,1] row_mask:0xf bank_mask:0xf
	v_mov_b32_dpp v173, v131 quad_perm:[2,3,0,1] row_mask:0xf bank_mask:0xf
	v_cndmask_b32_e64 v198, v194, v197, s[6:7]
	v_cndmask_b32_e64 v199, v196, v195, s[6:7]
	v_cndmask_b32_e64 v200, v130, v173, s[6:7]
	v_cndmask_b32_e64 v201, v172, v131, s[6:7]
	global_store_dwordx2 v[132:133], v[198:199], off offset:256
	global_store_dwordx2 v[134:135], v[200:201], off offset:256
	v_pk_mul_f32 v[140:141], v[52:53], v[162:163] op_sel_hi:[1,0]
	v_pk_mul_f32 v[142:143], v[54:55], v[162:163] op_sel_hi:[1,0]
	v_pk_mul_f32 v[200:201], v[48:49], v[162:163] op_sel_hi:[1,0]
	v_pk_mul_f32 v[202:203], v[50:51], v[162:163] op_sel_hi:[1,0]
	v_cvt_pk_bf16_f32 v190, v140, v141
	v_cvt_pk_bf16_f32 v191, v142, v143
	v_cvt_pk_bf16_f32 v204, v200, v201
	v_cvt_pk_bf16_f32 v205, v202, v203
	v_mov_b32_dpp v192, v190 quad_perm:[1,0,3,2] row_mask:0xf bank_mask:0xf
	v_mov_b32_dpp v193, v191 quad_perm:[1,0,3,2] row_mask:0xf bank_mask:0xf
	v_mov_b32_dpp v206, v204 quad_perm:[1,0,3,2] row_mask:0xf bank_mask:0xf
	v_mov_b32_dpp v207, v205 quad_perm:[1,0,3,2] row_mask:0xf bank_mask:0xf
	v_perm_b32 v194, v192, v190, v171
	v_perm_b32 v195, v193, v191, v171
	v_perm_b32 v130, v206, v204, v171
	v_perm_b32 v131, v207, v205, v171
	v_mov_b32_dpp v196, v194 quad_perm:[2,3,0,1] row_mask:0xf bank_mask:0xf
	v_mov_b32_dpp v197, v195 quad_perm:[2,3,0,1] row_mask:0xf bank_mask:0xf
	v_mov_b32_dpp v172, v130 quad_perm:[2,3,0,1] row_mask:0xf bank_mask:0xf
	v_mov_b32_dpp v173, v131 quad_perm:[2,3,0,1] row_mask:0xf bank_mask:0xf
	v_cndmask_b32_e64 v198, v194, v197, s[6:7]
	v_cndmask_b32_e64 v199, v196, v195, s[6:7]
	v_cndmask_b32_e64 v200, v130, v173, s[6:7]
	v_cndmask_b32_e64 v201, v172, v131, s[6:7]
	global_store_dwordx2 v[136:137], v[198:199], off offset:256
	global_store_dwordx2 v[138:139], v[200:201], off offset:256
	v_pk_mul_f32 v[140:141], v[44:45], v[162:163] op_sel:[0,1]
	v_pk_mul_f32 v[142:143], v[46:47], v[162:163] op_sel:[0,1]
	v_pk_mul_f32 v[200:201], v[40:41], v[162:163] op_sel:[0,1]
	v_pk_mul_f32 v[202:203], v[42:43], v[162:163] op_sel:[0,1]
	v_cvt_pk_bf16_f32 v190, v140, v141
	v_cvt_pk_bf16_f32 v191, v142, v143
	v_cvt_pk_bf16_f32 v204, v200, v201
	v_cvt_pk_bf16_f32 v205, v202, v203
	v_mov_b32_dpp v192, v190 quad_perm:[1,0,3,2] row_mask:0xf bank_mask:0xf
	v_mov_b32_dpp v193, v191 quad_perm:[1,0,3,2] row_mask:0xf bank_mask:0xf
	v_mov_b32_dpp v206, v204 quad_perm:[1,0,3,2] row_mask:0xf bank_mask:0xf
	v_mov_b32_dpp v207, v205 quad_perm:[1,0,3,2] row_mask:0xf bank_mask:0xf
	v_perm_b32 v194, v192, v190, v171
	v_perm_b32 v195, v193, v191, v171
	v_perm_b32 v130, v206, v204, v171
	v_perm_b32 v131, v207, v205, v171
	v_mov_b32_dpp v196, v194 quad_perm:[2,3,0,1] row_mask:0xf bank_mask:0xf
	v_mov_b32_dpp v197, v195 quad_perm:[2,3,0,1] row_mask:0xf bank_mask:0xf
	v_mov_b32_dpp v172, v130 quad_perm:[2,3,0,1] row_mask:0xf bank_mask:0xf
	v_mov_b32_dpp v173, v131 quad_perm:[2,3,0,1] row_mask:0xf bank_mask:0xf
	v_cndmask_b32_e64 v198, v194, v197, s[6:7]
	v_cndmask_b32_e64 v199, v196, v195, s[6:7]
	v_cndmask_b32_e64 v200, v130, v173, s[6:7]
	v_cndmask_b32_e64 v201, v172, v131, s[6:7]
	global_store_dwordx2 v[132:133], v[198:199], off offset:288
	global_store_dwordx2 v[134:135], v[200:201], off offset:288
	v_pk_mul_f32 v[140:141], v[36:37], v[162:163] op_sel:[0,1]
	v_pk_mul_f32 v[142:143], v[38:39], v[162:163] op_sel:[0,1]
	v_pk_mul_f32 v[200:201], v[32:33], v[162:163] op_sel:[0,1]
	v_pk_mul_f32 v[202:203], v[34:35], v[162:163] op_sel:[0,1]
	v_cvt_pk_bf16_f32 v190, v140, v141
	v_cvt_pk_bf16_f32 v191, v142, v143
	v_cvt_pk_bf16_f32 v204, v200, v201
	v_cvt_pk_bf16_f32 v205, v202, v203
	v_mov_b32_dpp v192, v190 quad_perm:[1,0,3,2] row_mask:0xf bank_mask:0xf
	v_mov_b32_dpp v193, v191 quad_perm:[1,0,3,2] row_mask:0xf bank_mask:0xf
	v_mov_b32_dpp v206, v204 quad_perm:[1,0,3,2] row_mask:0xf bank_mask:0xf
	v_mov_b32_dpp v207, v205 quad_perm:[1,0,3,2] row_mask:0xf bank_mask:0xf
	v_perm_b32 v194, v192, v190, v171
	v_perm_b32 v195, v193, v191, v171
	v_perm_b32 v130, v206, v204, v171
	v_perm_b32 v131, v207, v205, v171
	v_mov_b32_dpp v196, v194 quad_perm:[2,3,0,1] row_mask:0xf bank_mask:0xf
	v_mov_b32_dpp v197, v195 quad_perm:[2,3,0,1] row_mask:0xf bank_mask:0xf
	v_mov_b32_dpp v172, v130 quad_perm:[2,3,0,1] row_mask:0xf bank_mask:0xf
	v_mov_b32_dpp v173, v131 quad_perm:[2,3,0,1] row_mask:0xf bank_mask:0xf
	v_cndmask_b32_e64 v198, v194, v197, s[6:7]
	v_cndmask_b32_e64 v199, v196, v195, s[6:7]
	v_cndmask_b32_e64 v200, v130, v173, s[6:7]
	v_cndmask_b32_e64 v201, v172, v131, s[6:7]
	global_store_dwordx2 v[136:137], v[198:199], off offset:288
	global_store_dwordx2 v[138:139], v[200:201], off offset:288
	v_pk_mul_f32 v[140:141], v[28:29], v[128:129] op_sel_hi:[1,0]
	v_pk_mul_f32 v[142:143], v[30:31], v[128:129] op_sel_hi:[1,0]
	v_pk_mul_f32 v[200:201], v[24:25], v[128:129] op_sel_hi:[1,0]
	v_pk_mul_f32 v[202:203], v[26:27], v[128:129] op_sel_hi:[1,0]
	v_cvt_pk_bf16_f32 v190, v140, v141
	v_cvt_pk_bf16_f32 v191, v142, v143
	v_cvt_pk_bf16_f32 v204, v200, v201
	v_cvt_pk_bf16_f32 v205, v202, v203
	v_mov_b32_dpp v192, v190 quad_perm:[1,0,3,2] row_mask:0xf bank_mask:0xf
	v_mov_b32_dpp v193, v191 quad_perm:[1,0,3,2] row_mask:0xf bank_mask:0xf
	v_mov_b32_dpp v206, v204 quad_perm:[1,0,3,2] row_mask:0xf bank_mask:0xf
	v_mov_b32_dpp v207, v205 quad_perm:[1,0,3,2] row_mask:0xf bank_mask:0xf
	v_perm_b32 v194, v192, v190, v171
	v_perm_b32 v195, v193, v191, v171
	v_perm_b32 v130, v206, v204, v171
	v_perm_b32 v131, v207, v205, v171
	v_mov_b32_dpp v196, v194 quad_perm:[2,3,0,1] row_mask:0xf bank_mask:0xf
	v_mov_b32_dpp v197, v195 quad_perm:[2,3,0,1] row_mask:0xf bank_mask:0xf
	v_mov_b32_dpp v172, v130 quad_perm:[2,3,0,1] row_mask:0xf bank_mask:0xf
	v_mov_b32_dpp v173, v131 quad_perm:[2,3,0,1] row_mask:0xf bank_mask:0xf
	v_cndmask_b32_e64 v198, v194, v197, s[6:7]
	v_cndmask_b32_e64 v199, v196, v195, s[6:7]
	v_cndmask_b32_e64 v200, v130, v173, s[6:7]
	v_cndmask_b32_e64 v201, v172, v131, s[6:7]
	global_store_dwordx2 v[132:133], v[198:199], off offset:320
	global_store_dwordx2 v[134:135], v[200:201], off offset:320
	v_pk_mul_f32 v[140:141], v[20:21], v[128:129] op_sel_hi:[1,0]
	v_pk_mul_f32 v[142:143], v[22:23], v[128:129] op_sel_hi:[1,0]
	v_pk_mul_f32 v[200:201], v[16:17], v[128:129] op_sel_hi:[1,0]
	v_pk_mul_f32 v[202:203], v[18:19], v[128:129] op_sel_hi:[1,0]
	v_cvt_pk_bf16_f32 v190, v140, v141
	v_cvt_pk_bf16_f32 v191, v142, v143
	v_cvt_pk_bf16_f32 v204, v200, v201
	v_cvt_pk_bf16_f32 v205, v202, v203
	v_mov_b32_dpp v192, v190 quad_perm:[1,0,3,2] row_mask:0xf bank_mask:0xf
	v_mov_b32_dpp v193, v191 quad_perm:[1,0,3,2] row_mask:0xf bank_mask:0xf
	v_mov_b32_dpp v206, v204 quad_perm:[1,0,3,2] row_mask:0xf bank_mask:0xf
	v_mov_b32_dpp v207, v205 quad_perm:[1,0,3,2] row_mask:0xf bank_mask:0xf
	v_perm_b32 v194, v192, v190, v171
	v_perm_b32 v195, v193, v191, v171
	v_perm_b32 v130, v206, v204, v171
	v_perm_b32 v131, v207, v205, v171
	v_mov_b32_dpp v196, v194 quad_perm:[2,3,0,1] row_mask:0xf bank_mask:0xf
	v_mov_b32_dpp v197, v195 quad_perm:[2,3,0,1] row_mask:0xf bank_mask:0xf
	v_mov_b32_dpp v172, v130 quad_perm:[2,3,0,1] row_mask:0xf bank_mask:0xf
	v_mov_b32_dpp v173, v131 quad_perm:[2,3,0,1] row_mask:0xf bank_mask:0xf
	v_cndmask_b32_e64 v198, v194, v197, s[6:7]
	v_cndmask_b32_e64 v199, v196, v195, s[6:7]
	v_cndmask_b32_e64 v200, v130, v173, s[6:7]
	v_cndmask_b32_e64 v201, v172, v131, s[6:7]
	global_store_dwordx2 v[136:137], v[198:199], off offset:320
	global_store_dwordx2 v[138:139], v[200:201], off offset:320
	v_pk_mul_f32 v[140:141], v[12:13], v[128:129] op_sel:[0,1]
	v_pk_mul_f32 v[142:143], v[14:15], v[128:129] op_sel:[0,1]
	v_pk_mul_f32 v[200:201], v[8:9], v[128:129] op_sel:[0,1]
	v_pk_mul_f32 v[202:203], v[10:11], v[128:129] op_sel:[0,1]
	v_cvt_pk_bf16_f32 v190, v140, v141
	v_cvt_pk_bf16_f32 v191, v142, v143
	v_cvt_pk_bf16_f32 v204, v200, v201
	v_cvt_pk_bf16_f32 v205, v202, v203
	v_mov_b32_dpp v192, v190 quad_perm:[1,0,3,2] row_mask:0xf bank_mask:0xf
	v_mov_b32_dpp v193, v191 quad_perm:[1,0,3,2] row_mask:0xf bank_mask:0xf
	v_mov_b32_dpp v206, v204 quad_perm:[1,0,3,2] row_mask:0xf bank_mask:0xf
	v_mov_b32_dpp v207, v205 quad_perm:[1,0,3,2] row_mask:0xf bank_mask:0xf
	v_perm_b32 v194, v192, v190, v171
	v_perm_b32 v195, v193, v191, v171
	v_perm_b32 v130, v206, v204, v171
	v_perm_b32 v131, v207, v205, v171
	v_mov_b32_dpp v196, v194 quad_perm:[2,3,0,1] row_mask:0xf bank_mask:0xf
	v_mov_b32_dpp v197, v195 quad_perm:[2,3,0,1] row_mask:0xf bank_mask:0xf
	v_mov_b32_dpp v172, v130 quad_perm:[2,3,0,1] row_mask:0xf bank_mask:0xf
	v_mov_b32_dpp v173, v131 quad_perm:[2,3,0,1] row_mask:0xf bank_mask:0xf
	v_cndmask_b32_e64 v198, v194, v197, s[6:7]
	v_cndmask_b32_e64 v199, v196, v195, s[6:7]
	v_cndmask_b32_e64 v200, v130, v173, s[6:7]
	v_cndmask_b32_e64 v201, v172, v131, s[6:7]
	global_store_dwordx2 v[132:133], v[198:199], off offset:352
	global_store_dwordx2 v[134:135], v[200:201], off offset:352
	v_pk_mul_f32 v[140:141], v[4:5], v[128:129] op_sel:[0,1]
	v_pk_mul_f32 v[142:143], v[6:7], v[128:129] op_sel:[0,1]
	v_pk_mul_f32 v[200:201], v[0:1], v[128:129] op_sel:[0,1]
	v_pk_mul_f32 v[202:203], v[2:3], v[128:129] op_sel:[0,1]
	v_cvt_pk_bf16_f32 v190, v140, v141
	v_cvt_pk_bf16_f32 v191, v142, v143
	v_cvt_pk_bf16_f32 v204, v200, v201
	v_cvt_pk_bf16_f32 v205, v202, v203
	v_mov_b32_dpp v192, v190 quad_perm:[1,0,3,2] row_mask:0xf bank_mask:0xf
	v_mov_b32_dpp v193, v191 quad_perm:[1,0,3,2] row_mask:0xf bank_mask:0xf
	v_mov_b32_dpp v206, v204 quad_perm:[1,0,3,2] row_mask:0xf bank_mask:0xf
	v_mov_b32_dpp v207, v205 quad_perm:[1,0,3,2] row_mask:0xf bank_mask:0xf
	v_perm_b32 v194, v192, v190, v171
	v_perm_b32 v195, v193, v191, v171
	v_perm_b32 v130, v206, v204, v171
	v_perm_b32 v131, v207, v205, v171
	v_mov_b32_dpp v196, v194 quad_perm:[2,3,0,1] row_mask:0xf bank_mask:0xf
	v_mov_b32_dpp v197, v195 quad_perm:[2,3,0,1] row_mask:0xf bank_mask:0xf
	v_mov_b32_dpp v172, v130 quad_perm:[2,3,0,1] row_mask:0xf bank_mask:0xf
	v_mov_b32_dpp v173, v131 quad_perm:[2,3,0,1] row_mask:0xf bank_mask:0xf
	v_cndmask_b32_e64 v198, v194, v197, s[6:7]
	v_cndmask_b32_e64 v199, v196, v195, s[6:7]
	v_cndmask_b32_e64 v200, v130, v173, s[6:7]
	v_cndmask_b32_e64 v201, v172, v131, s[6:7]
	global_store_dwordx2 v[136:137], v[198:199], off offset:352
	global_store_dwordx2 v[138:139], v[200:201], off offset:352
	s_movk_i32 s69, 0x4000

.LBB0_512:
	v_lshl_add_u64 v[16:17], v[12:13], 0, v[4:5]
	v_add_co_u32_e32 v16, vcc, 0x18d00000, v16
	v_lshl_add_u64 v[88:89], v[14:15], 0, v[4:5]
	s_nop 0
	v_addc_co_u32_e32 v17, vcc, 0, v17, vcc
	global_load_dwordx4 v[20:23], v[16:17], off offset:0
	global_load_dwordx4 v[90:93], v[88:89], off offset:-512
	global_load_dwordx4 v[24:27], v[16:17], off offset:64
	global_load_dwordx4 v[94:97], v[88:89], off offset:-448
	global_load_dwordx4 v[28:31], v[16:17], off offset:128
	global_load_dwordx4 v[98:101], v[88:89], off offset:-384
	global_load_dwordx4 v[32:35], v[16:17], off offset:192
	global_load_dwordx4 v[102:105], v[88:89], off offset:-320
	global_load_dwordx4 v[36:39], v[16:17], off offset:256
	global_load_dwordx4 v[106:109], v[88:89], off offset:-256
	global_load_dwordx4 v[40:43], v[16:17], off offset:320
	global_load_dwordx4 v[110:113], v[88:89], off offset:-192
	global_load_dwordx4 v[44:47], v[16:17], off offset:384
	global_load_dwordx4 v[114:117], v[88:89], off offset:-128
	global_load_dwordx4 v[48:51], v[16:17], off offset:448
	global_load_dwordx4 v[118:121], v[88:89], off offset:-64
	global_load_dwordx4 v[52:55], v[16:17], off offset:512
	global_load_dwordx4 v[122:125], v[88:89], off offset:0
	global_load_dwordx4 v[56:59], v[16:17], off offset:576
	global_load_dwordx4 v[126:129], v[88:89], off offset:64
	global_load_dwordx4 v[60:63], v[16:17], off offset:640
	global_load_dwordx4 v[130:133], v[88:89], off offset:128
	global_load_dwordx4 v[64:67], v[16:17], off offset:704
	global_load_dwordx4 v[134:137], v[88:89], off offset:192
	global_load_dwordx4 v[68:71], v[16:17], off offset:768
	global_load_dwordx4 v[138:141], v[88:89], off offset:256
	global_load_dwordx4 v[72:75], v[16:17], off offset:832
	global_load_dwordx4 v[142:145], v[88:89], off offset:320
	global_load_dwordx4 v[76:79], v[16:17], off offset:896
	global_load_dwordx4 v[146:149], v[88:89], off offset:384
	global_load_dwordx4 v[80:83], v[16:17], off offset:960
	global_load_dwordx4 v[150:153], v[88:89], off offset:448
	s_waitcnt vmcnt(30)
	v_mfma_f32_16x16x32_bf16 v[0:3], v[20:23], v[90:93], v[0:3]
	global_load_dwordx4 v[20:23], v[16:17], off offset:1024
	global_load_dwordx4 v[90:93], v[88:89], off offset:512
	s_waitcnt vmcnt(30)
	v_mfma_f32_16x16x32_bf16 v[0:3], v[24:27], v[94:97], v[0:3]
	global_load_dwordx4 v[24:27], v[16:17], off offset:1088
	global_load_dwordx4 v[94:97], v[88:89], off offset:576
	s_waitcnt vmcnt(30)
	v_mfma_f32_16x16x32_bf16 v[0:3], v[28:31], v[98:101], v[0:3]
	global_load_dwordx4 v[28:31], v[16:17], off offset:1152
	global_load_dwordx4 v[98:101], v[88:89], off offset:640
	s_waitcnt vmcnt(30)
	v_mfma_f32_16x16x32_bf16 v[0:3], v[32:35], v[102:105], v[0:3]
	global_load_dwordx4 v[32:35], v[16:17], off offset:1216
	global_load_dwordx4 v[102:105], v[88:89], off offset:704
	s_waitcnt vmcnt(30)
	v_mfma_f32_16x16x32_bf16 v[0:3], v[36:39], v[106:109], v[0:3]
	global_load_dwordx4 v[36:39], v[16:17], off offset:1280
	global_load_dwordx4 v[106:109], v[88:89], off offset:768
	s_waitcnt vmcnt(30)
	v_mfma_f32_16x16x32_bf16 v[0:3], v[40:43], v[110:113], v[0:3]
	global_load_dwordx4 v[40:43], v[16:17], off offset:1344
	global_load_dwordx4 v[110:113], v[88:89], off offset:832
	s_waitcnt vmcnt(30)
	v_mfma_f32_16x16x32_bf16 v[0:3], v[44:47], v[114:117], v[0:3]
	global_load_dwordx4 v[44:47], v[16:17], off offset:1408
	global_load_dwordx4 v[114:117], v[88:89], off offset:896
	s_waitcnt vmcnt(30)
	v_mfma_f32_16x16x32_bf16 v[0:3], v[48:51], v[118:121], v[0:3]
	global_load_dwordx4 v[48:51], v[16:17], off offset:1472
	global_load_dwordx4 v[118:121], v[88:89], off offset:960
	s_waitcnt vmcnt(30)
	v_mfma_f32_16x16x32_bf16 v[0:3], v[52:55], v[122:125], v[0:3]
	global_load_dwordx4 v[52:55], v[16:17], off offset:1536
	global_load_dwordx4 v[122:125], v[88:89], off offset:1024
	s_waitcnt vmcnt(30)
	v_mfma_f32_16x16x32_bf16 v[0:3], v[56:59], v[126:129], v[0:3]
	global_load_dwordx4 v[56:59], v[16:17], off offset:1600
	global_load_dwordx4 v[126:129], v[88:89], off offset:1088
	s_waitcnt vmcnt(30)
	v_mfma_f32_16x16x32_bf16 v[0:3], v[60:63], v[130:133], v[0:3]
	global_load_dwordx4 v[60:63], v[16:17], off offset:1664
	global_load_dwordx4 v[130:133], v[88:89], off offset:1152
	s_waitcnt vmcnt(30)
	v_mfma_f32_16x16x32_bf16 v[0:3], v[64:67], v[134:137], v[0:3]
	global_load_dwordx4 v[64:67], v[16:17], off offset:1728
	global_load_dwordx4 v[134:137], v[88:89], off offset:1216
	s_waitcnt vmcnt(30)
	v_mfma_f32_16x16x32_bf16 v[0:3], v[68:71], v[138:141], v[0:3]
	global_load_dwordx4 v[68:71], v[16:17], off offset:1792
	global_load_dwordx4 v[138:141], v[88:89], off offset:1280
	s_waitcnt vmcnt(30)
	v_mfma_f32_16x16x32_bf16 v[0:3], v[72:75], v[142:145], v[0:3]
	global_load_dwordx4 v[72:75], v[16:17], off offset:1856
	global_load_dwordx4 v[142:145], v[88:89], off offset:1344
	s_waitcnt vmcnt(30)
	v_mfma_f32_16x16x32_bf16 v[0:3], v[76:79], v[146:149], v[0:3]
	global_load_dwordx4 v[76:79], v[16:17], off offset:1920
	global_load_dwordx4 v[146:149], v[88:89], off offset:1408
	s_waitcnt vmcnt(30)
	v_mfma_f32_16x16x32_bf16 v[0:3], v[80:83], v[150:153], v[0:3]
	global_load_dwordx4 v[80:83], v[16:17], off offset:1984
	global_load_dwordx4 v[150:153], v[88:89], off offset:1472
	s_waitcnt vmcnt(30)
	v_mfma_f32_16x16x32_bf16 v[0:3], v[20:23], v[90:93], v[0:3]
	global_load_dwordx4 v[20:23], v[16:17], off offset:2048
	global_load_dwordx4 v[90:93], v[88:89], off offset:1536
	s_waitcnt vmcnt(30)
	v_mfma_f32_16x16x32_bf16 v[0:3], v[24:27], v[94:97], v[0:3]
	global_load_dwordx4 v[24:27], v[16:17], off offset:2112
	global_load_dwordx4 v[94:97], v[88:89], off offset:1600
	s_waitcnt vmcnt(30)
	v_mfma_f32_16x16x32_bf16 v[0:3], v[28:31], v[98:101], v[0:3]
	global_load_dwordx4 v[28:31], v[16:17], off offset:2176
	global_load_dwordx4 v[98:101], v[88:89], off offset:1664
	s_waitcnt vmcnt(30)
	v_mfma_f32_16x16x32_bf16 v[0:3], v[32:35], v[102:105], v[0:3]
	global_load_dwordx4 v[32:35], v[16:17], off offset:2240
	global_load_dwordx4 v[102:105], v[88:89], off offset:1728
	s_waitcnt vmcnt(30)
	v_mfma_f32_16x16x32_bf16 v[0:3], v[36:39], v[106:109], v[0:3]
	global_load_dwordx4 v[36:39], v[16:17], off offset:2304
	global_load_dwordx4 v[106:109], v[88:89], off offset:1792
	s_waitcnt vmcnt(30)
	v_mfma_f32_16x16x32_bf16 v[0:3], v[40:43], v[110:113], v[0:3]
	global_load_dwordx4 v[40:43], v[16:17], off offset:2368
	global_load_dwordx4 v[110:113], v[88:89], off offset:1856
	s_waitcnt vmcnt(30)
	v_mfma_f32_16x16x32_bf16 v[0:3], v[44:47], v[114:117], v[0:3]
	global_load_dwordx4 v[44:47], v[16:17], off offset:2432
	global_load_dwordx4 v[114:117], v[88:89], off offset:1920
	s_waitcnt vmcnt(30)
	v_mfma_f32_16x16x32_bf16 v[0:3], v[48:51], v[118:121], v[0:3]
	global_load_dwordx4 v[48:51], v[16:17], off offset:2496
	global_load_dwordx4 v[118:121], v[88:89], off offset:1984
	s_waitcnt vmcnt(30)
	v_mfma_f32_16x16x32_bf16 v[0:3], v[52:55], v[122:125], v[0:3]
	global_load_dwordx4 v[52:55], v[16:17], off offset:2560
	global_load_dwordx4 v[122:125], v[88:89], off offset:2048
	s_waitcnt vmcnt(30)
	v_mfma_f32_16x16x32_bf16 v[0:3], v[56:59], v[126:129], v[0:3]
	global_load_dwordx4 v[56:59], v[16:17], off offset:2624
	global_load_dwordx4 v[126:129], v[88:89], off offset:2112
	s_waitcnt vmcnt(30)
	v_mfma_f32_16x16x32_bf16 v[0:3], v[60:63], v[130:133], v[0:3]
	global_load_dwordx4 v[60:63], v[16:17], off offset:2688
	global_load_dwordx4 v[130:133], v[88:89], off offset:2176
	s_waitcnt vmcnt(30)
	v_mfma_f32_16x16x32_bf16 v[0:3], v[64:67], v[134:137], v[0:3]
	global_load_dwordx4 v[64:67], v[16:17], off offset:2752
	global_load_dwordx4 v[134:137], v[88:89], off offset:2240
	s_waitcnt vmcnt(30)
	v_mfma_f32_16x16x32_bf16 v[0:3], v[68:71], v[138:141], v[0:3]
	global_load_dwordx4 v[68:71], v[16:17], off offset:2816
	global_load_dwordx4 v[138:141], v[88:89], off offset:2304
	s_waitcnt vmcnt(30)
	v_mfma_f32_16x16x32_bf16 v[0:3], v[72:75], v[142:145], v[0:3]
	global_load_dwordx4 v[72:75], v[16:17], off offset:2880
	global_load_dwordx4 v[142:145], v[88:89], off offset:2368
	s_waitcnt vmcnt(30)
	v_mfma_f32_16x16x32_bf16 v[0:3], v[76:79], v[146:149], v[0:3]
	global_load_dwordx4 v[76:79], v[16:17], off offset:2944
	global_load_dwordx4 v[146:149], v[88:89], off offset:2432
	s_waitcnt vmcnt(30)
	v_mfma_f32_16x16x32_bf16 v[0:3], v[80:83], v[150:153], v[0:3]
	global_load_dwordx4 v[80:83], v[16:17], off offset:3008
	global_load_dwordx4 v[150:153], v[88:89], off offset:2496
	s_waitcnt vmcnt(30)
	v_mfma_f32_16x16x32_bf16 v[0:3], v[20:23], v[90:93], v[0:3]
	global_load_dwordx4 v[20:23], v[16:17], off offset:3072
	global_load_dwordx4 v[90:93], v[88:89], off offset:2560
	s_waitcnt vmcnt(30)
	v_mfma_f32_16x16x32_bf16 v[0:3], v[24:27], v[94:97], v[0:3]
	global_load_dwordx4 v[24:27], v[16:17], off offset:3136
	global_load_dwordx4 v[94:97], v[88:89], off offset:2624
	s_waitcnt vmcnt(30)
	v_mfma_f32_16x16x32_bf16 v[0:3], v[28:31], v[98:101], v[0:3]
	global_load_dwordx4 v[28:31], v[16:17], off offset:3200
	global_load_dwordx4 v[98:101], v[88:89], off offset:2688
	s_waitcnt vmcnt(30)
	v_mfma_f32_16x16x32_bf16 v[0:3], v[32:35], v[102:105], v[0:3]
	global_load_dwordx4 v[32:35], v[16:17], off offset:3264
	global_load_dwordx4 v[102:105], v[88:89], off offset:2752
	s_waitcnt vmcnt(30)
	v_mfma_f32_16x16x32_bf16 v[0:3], v[36:39], v[106:109], v[0:3]
	global_load_dwordx4 v[36:39], v[16:17], off offset:3328
	global_load_dwordx4 v[106:109], v[88:89], off offset:2816
	s_waitcnt vmcnt(30)
	v_mfma_f32_16x16x32_bf16 v[0:3], v[40:43], v[110:113], v[0:3]
	global_load_dwordx4 v[40:43], v[16:17], off offset:3392
	global_load_dwordx4 v[110:113], v[88:89], off offset:2880
	s_waitcnt vmcnt(30)
	v_mfma_f32_16x16x32_bf16 v[0:3], v[44:47], v[114:117], v[0:3]
	global_load_dwordx4 v[44:47], v[16:17], off offset:3456
	global_load_dwordx4 v[114:117], v[88:89], off offset:2944
	s_waitcnt vmcnt(30)
	v_mfma_f32_16x16x32_bf16 v[0:3], v[48:51], v[118:121], v[0:3]
	global_load_dwordx4 v[48:51], v[16:17], off offset:3520
	global_load_dwordx4 v[118:121], v[88:89], off offset:3008
	s_waitcnt vmcnt(30)
	v_mfma_f32_16x16x32_bf16 v[0:3], v[52:55], v[122:125], v[0:3]
	global_load_dwordx4 v[52:55], v[16:17], off offset:3584
	global_load_dwordx4 v[122:125], v[88:89], off offset:3072
	s_waitcnt vmcnt(30)
	v_mfma_f32_16x16x32_bf16 v[0:3], v[56:59], v[126:129], v[0:3]
	global_load_dwordx4 v[56:59], v[16:17], off offset:3648
	global_load_dwordx4 v[126:129], v[88:89], off offset:3136
	s_waitcnt vmcnt(30)
	v_mfma_f32_16x16x32_bf16 v[0:3], v[60:63], v[130:133], v[0:3]
	global_load_dwordx4 v[60:63], v[16:17], off offset:3712
	global_load_dwordx4 v[130:133], v[88:89], off offset:3200
	s_waitcnt vmcnt(30)
	v_mfma_f32_16x16x32_bf16 v[0:3], v[64:67], v[134:137], v[0:3]
	global_load_dwordx4 v[64:67], v[16:17], off offset:3776
	global_load_dwordx4 v[134:137], v[88:89], off offset:3264
	s_waitcnt vmcnt(30)
	v_mfma_f32_16x16x32_bf16 v[0:3], v[68:71], v[138:141], v[0:3]
	global_load_dwordx4 v[68:71], v[16:17], off offset:3840
	global_load_dwordx4 v[138:141], v[88:89], off offset:3328
	s_waitcnt vmcnt(30)
	v_mfma_f32_16x16x32_bf16 v[0:3], v[72:75], v[142:145], v[0:3]
	global_load_dwordx4 v[72:75], v[16:17], off offset:3904
	global_load_dwordx4 v[142:145], v[88:89], off offset:3392
	s_waitcnt vmcnt(30)
	v_mfma_f32_16x16x32_bf16 v[0:3], v[76:79], v[146:149], v[0:3]
	global_load_dwordx4 v[76:79], v[16:17], off offset:3968
	global_load_dwordx4 v[146:149], v[88:89], off offset:3456
	s_waitcnt vmcnt(30)
	v_mfma_f32_16x16x32_bf16 v[0:3], v[80:83], v[150:153], v[0:3]
	global_load_dwordx4 v[80:83], v[16:17], off offset:4032
	global_load_dwordx4 v[150:153], v[88:89], off offset:3520
	s_waitcnt vmcnt(30)
	v_mfma_f32_16x16x32_bf16 v[0:3], v[20:23], v[90:93], v[0:3]
	s_waitcnt vmcnt(28)
	v_mfma_f32_16x16x32_bf16 v[0:3], v[24:27], v[94:97], v[0:3]
	s_waitcnt vmcnt(26)
	v_mfma_f32_16x16x32_bf16 v[0:3], v[28:31], v[98:101], v[0:3]
	s_waitcnt vmcnt(24)
	v_mfma_f32_16x16x32_bf16 v[0:3], v[32:35], v[102:105], v[0:3]
	s_waitcnt vmcnt(22)
	v_mfma_f32_16x16x32_bf16 v[0:3], v[36:39], v[106:109], v[0:3]
	s_waitcnt vmcnt(20)
	v_mfma_f32_16x16x32_bf16 v[0:3], v[40:43], v[110:113], v[0:3]
	s_waitcnt vmcnt(18)
	v_mfma_f32_16x16x32_bf16 v[0:3], v[44:47], v[114:117], v[0:3]
	s_waitcnt vmcnt(16)
	v_mfma_f32_16x16x32_bf16 v[0:3], v[48:51], v[118:121], v[0:3]
	s_waitcnt vmcnt(14)
	v_mfma_f32_16x16x32_bf16 v[0:3], v[52:55], v[122:125], v[0:3]
	s_waitcnt vmcnt(12)
	v_mfma_f32_16x16x32_bf16 v[0:3], v[56:59], v[126:129], v[0:3]
	s_waitcnt vmcnt(10)
	v_mfma_f32_16x16x32_bf16 v[0:3], v[60:63], v[130:133], v[0:3]
	s_waitcnt vmcnt(8)
	v_mfma_f32_16x16x32_bf16 v[0:3], v[64:67], v[134:137], v[0:3]
	s_waitcnt vmcnt(6)
	v_mfma_f32_16x16x32_bf16 v[0:3], v[68:71], v[138:141], v[0:3]
	s_waitcnt vmcnt(4)
	v_mfma_f32_16x16x32_bf16 v[0:3], v[72:75], v[142:145], v[0:3]
	s_waitcnt vmcnt(2)
	v_mfma_f32_16x16x32_bf16 v[0:3], v[76:79], v[146:149], v[0:3]
	s_waitcnt vmcnt(0)
	v_mfma_f32_16x16x32_bf16 v[0:3], v[80:83], v[150:153], v[0:3]
	s_lshl_b32 s3, s2, 6
	v_or3_b32 v14, s3, v18, v19
	v_ashrrev_i32_e32 v15, 31, v14
	v_lshlrev_b64 v[12:13], 7, v[14:15]
	v_lshl_add_u64 v[12:13], s[8:9], 0, v[12:13]
	global_load_dwordx4 v[20:23], v[12:13], off offset:48
	global_load_dwordx4 v[24:27], v[12:13], off offset:32
	global_load_dwordx4 v[28:31], v[12:13], off
	global_load_dwordx4 v[32:35], v[12:13], off offset:16
	s_add_i32 s2, s2, s90
	v_add_u32_e32 v6, s7, v6
	s_cmpk_gt_i32 s2, 0xff
	s_waitcnt vmcnt(3)
	v_add_f32_e32 v38, v20, v21
	v_add_f32_e32 v40, v22, v23
	s_waitcnt vmcnt(1)
	v_mov_b32_e32 v16, v28
	s_waitcnt vmcnt(0)
	v_mov_b32_e32 v17, v32
	v_mov_b32_e32 v32, v29
	v_mov_b32_e32 v28, v30
	v_mov_b32_e32 v29, v34
	v_mov_b32_e32 v34, v31
	v_pk_add_f32 v[16:17], v[16:17], v[32:33]
	v_pk_add_f32 v[28:29], v[28:29], v[34:35]
	s_nop 0
	v_pk_add_f32 v[16:17], v[16:17], v[28:29]
	v_mov_b32_e32 v28, v25
	v_mov_b32_e32 v29, v26
	v_mov_b32_e32 v25, v27
	v_pk_add_f32 v[24:25], v[28:29], v[24:25]
	v_add_f32_e32 v7, 0, v16
	v_pk_add_f32 v[36:37], v[24:25], v[24:25] op_sel:[0,1] op_sel_hi:[1,0]
	global_load_dwordx4 v[20:23], v[12:13], off offset:112
	global_load_dwordx4 v[24:27], v[12:13], off offset:96
	global_load_dwordx4 v[28:31], v[12:13], off offset:80
	global_load_dwordx4 v[32:35], v[12:13], off offset:64
	v_add_f32_e32 v16, v7, v17
	s_waitcnt vmcnt(2)
	v_add_f32_e32 v24, v24, v25
	v_add_f32_e32 v26, v26, v27
	s_waitcnt vmcnt(0)
	v_mov_b32_e32 v17, v32
	v_mov_b32_e32 v37, v33
	v_mov_b32_e32 v39, v34
	v_mov_b32_e32 v41, v35
	v_pk_add_f32 v[12:13], v[16:17], v[36:37]
	v_pk_add_f32 v[16:17], v[38:39], v[40:41]
	v_mov_b32_e32 v25, v22
	v_pk_add_f32 v[12:13], v[12:13], v[16:17]
	v_mov_b32_e32 v16, v29
	v_mov_b32_e32 v17, v30
	v_mov_b32_e32 v29, v31
	v_pk_add_f32 v[16:17], v[16:17], v[28:29]
	v_pk_add_f32 v[12:13], v[12:13], v[12:13] op_sel:[0,1] op_sel_hi:[1,0]
	v_pk_add_f32 v[16:17], v[16:17], v[16:17] op_sel:[0,1] op_sel_hi:[1,0]
	v_mov_b32_e32 v13, v20
	v_mov_b32_e32 v17, v21
	v_mov_b32_e32 v27, v23
	v_pk_add_f32 v[12:13], v[12:13], v[16:17]
	v_pk_add_f32 v[16:17], v[24:25], v[26:27]
	s_nop 0
	v_pk_add_f32 v[12:13], v[12:13], v[16:17]
	s_nop 0
	v_add_f32_e32 v7, v12, v13
	v_fmamk_f32 v7, v7, 0x3a000000, v222
	v_cmp_gt_f32_e32 vcc, s33, v7
	v_mul_f32_e32 v12, 0x4b800000, v7
	s_nop 0
	v_cndmask_b32_e32 v7, v7, v12, vcc
	v_rsq_f32_e32 v7, v7
	s_nop 0
	v_mul_f32_e32 v12, 0x45800000, v7
	v_cndmask_b32_e32 v7, v7, v12, vcc
	v_mov_b64_e32 v[12:13], s[64:65]
	v_mad_i64_i32 v[16:17], s[4:5], v14, s96, v[12:13]
	v_lshl_add_u64 v[16:17], v[16:17], 0, v[10:11]
	v_lshl_add_u64 v[16:17], v[16:17], 0, v[176:177]
	v_mul_f32_e32 v0, v0, v7
	v_add_co_u32_e32 v16, vcc, s31, v16
	v_cvt_pk_bf16_f32 v0, v0, s0
	s_nop 0
	v_addc_co_u32_e32 v17, vcc, 0, v17, vcc
	global_store_short v[16:17], v0, off offset:2048
	v_or_b32_e32 v16, 1, v14
	v_ashrrev_i32_e32 v17, 31, v16
	v_lshlrev_b64 v[20:21], 7, v[16:17]
	v_lshl_add_u64 v[36:37], s[8:9], 0, v[20:21]
	global_load_dwordx4 v[20:23], v[36:37], off offset:48
	global_load_dwordx4 v[24:27], v[36:37], off offset:32
	global_load_dwordx4 v[28:31], v[36:37], off
	global_load_dwordx4 v[32:35], v[36:37], off offset:16
	s_waitcnt vmcnt(3)
	v_add_f32_e32 v42, v20, v21
	v_add_f32_e32 v44, v22, v23
	s_waitcnt vmcnt(1)
	v_mov_b32_e32 v38, v28
	s_waitcnt vmcnt(0)
	v_mov_b32_e32 v39, v32
	v_mov_b32_e32 v32, v29
	v_pk_add_f32 v[28:29], v[38:39], v[32:33]
	v_mov_b32_e32 v32, v30
	v_mov_b32_e32 v33, v34
	v_mov_b32_e32 v34, v31
	v_pk_add_f32 v[30:31], v[32:33], v[34:35]
	s_nop 0
	v_pk_add_f32 v[28:29], v[28:29], v[30:31]
	s_nop 0
	v_add_f32_e32 v0, 0, v28
	v_add_f32_e32 v38, v0, v29
	v_mov_b32_e32 v28, v25
	v_mov_b32_e32 v29, v26
	v_mov_b32_e32 v25, v27
	v_pk_add_f32 v[24:25], v[28:29], v[24:25]
	s_nop 0
	v_pk_add_f32 v[40:41], v[24:25], v[24:25] op_sel:[0,1] op_sel_hi:[1,0]
	global_load_dwordx4 v[20:23], v[36:37], off offset:112
	global_load_dwordx4 v[24:27], v[36:37], off offset:96
	global_load_dwordx4 v[28:31], v[36:37], off offset:80
	global_load_dwordx4 v[32:35], v[36:37], off offset:64
	s_waitcnt vmcnt(2)
	v_add_f32_e32 v24, v24, v25
	v_add_f32_e32 v26, v26, v27
	s_waitcnt vmcnt(0)
	v_mov_b32_e32 v39, v32
	v_mov_b32_e32 v41, v33
	v_mov_b32_e32 v43, v34
	v_mov_b32_e32 v45, v35
	v_pk_add_f32 v[32:33], v[38:39], v[40:41]
	v_pk_add_f32 v[34:35], v[42:43], v[44:45]
	v_mov_b32_e32 v25, v22
	v_pk_add_f32 v[32:33], v[32:33], v[34:35]
	v_mov_b32_e32 v34, v29
	v_mov_b32_e32 v35, v30
	v_mov_b32_e32 v29, v31
	v_pk_add_f32 v[28:29], v[34:35], v[28:29]
	v_pk_add_f32 v[32:33], v[32:33], v[32:33] op_sel:[0,1] op_sel_hi:[1,0]
	v_pk_add_f32 v[28:29], v[28:29], v[28:29] op_sel:[0,1] op_sel_hi:[1,0]
	v_mov_b32_e32 v33, v20
	v_mov_b32_e32 v29, v21
	v_mov_b32_e32 v27, v23
	v_pk_add_f32 v[20:21], v[32:33], v[28:29]
	v_pk_add_f32 v[22:23], v[24:25], v[26:27]
	s_nop 0
	v_pk_add_f32 v[20:21], v[20:21], v[22:23]
	s_nop 0
	v_add_f32_e32 v0, v20, v21
	v_fmamk_f32 v0, v0, 0x3a000000, v222
	v_cmp_gt_f32_e32 vcc, s33, v0
	v_mul_f32_e32 v7, 0x4b800000, v0
	s_nop 0
	v_cndmask_b32_e32 v0, v0, v7, vcc
	v_rsq_f32_e32 v0, v0
	s_nop 0
	v_mul_f32_e32 v7, 0x45800000, v0
	v_cndmask_b32_e32 v0, v0, v7, vcc
	v_mul_f32_e32 v0, v1, v0
	v_cvt_pk_bf16_f32 v7, v0, s0
	v_mad_i64_i32 v[0:1], s[4:5], v16, s96, v[12:13]
	v_lshl_add_u64 v[0:1], v[0:1], 0, v[10:11]
	v_lshl_add_u64 v[0:1], v[0:1], 0, v[176:177]
	v_add_co_u32_e32 v0, vcc, s31, v0
	s_nop 1
	v_addc_co_u32_e32 v1, vcc, 0, v1, vcc
	global_store_short v[0:1], v7, off offset:2048
	v_or_b32_e32 v0, 2, v14
	v_ashrrev_i32_e32 v1, 31, v0
	v_lshlrev_b64 v[16:17], 7, v[0:1]
	v_lshl_add_u64 v[16:17], s[8:9], 0, v[16:17]
	global_load_dwordx4 v[20:23], v[16:17], off offset:48
	global_load_dwordx4 v[24:27], v[16:17], off offset:32
	global_load_dwordx4 v[28:31], v[16:17], off
	global_load_dwordx4 v[32:35], v[16:17], off offset:16
	s_waitcnt vmcnt(3)
	v_add_f32_e32 v40, v20, v21
	v_add_f32_e32 v42, v22, v23
	s_waitcnt vmcnt(1)
	v_mov_b32_e32 v36, v28
	s_waitcnt vmcnt(0)
	v_mov_b32_e32 v37, v32
	v_mov_b32_e32 v32, v29
	v_pk_add_f32 v[28:29], v[36:37], v[32:33]
	v_mov_b32_e32 v32, v30
	v_mov_b32_e32 v33, v34
	v_mov_b32_e32 v34, v31
	v_pk_add_f32 v[30:31], v[32:33], v[34:35]
	s_nop 0
	v_pk_add_f32 v[28:29], v[28:29], v[30:31]
	s_nop 0
	v_add_f32_e32 v1, 0, v28
	v_add_f32_e32 v36, v1, v29
	v_mov_b32_e32 v28, v25
	v_mov_b32_e32 v29, v26
	v_mov_b32_e32 v25, v27
	v_pk_add_f32 v[24:25], v[28:29], v[24:25]
	s_nop 0
	v_pk_add_f32 v[38:39], v[24:25], v[24:25] op_sel:[0,1] op_sel_hi:[1,0]
	global_load_dwordx4 v[20:23], v[16:17], off offset:112
	global_load_dwordx4 v[24:27], v[16:17], off offset:96
	global_load_dwordx4 v[28:31], v[16:17], off offset:80
	global_load_dwordx4 v[32:35], v[16:17], off offset:64
	s_waitcnt vmcnt(2)
	v_add_f32_e32 v24, v24, v25
	v_add_f32_e32 v26, v26, v27
	s_waitcnt vmcnt(0)
	v_mov_b32_e32 v37, v32
	v_mov_b32_e32 v39, v33
	v_mov_b32_e32 v41, v34
	v_mov_b32_e32 v43, v35
	v_pk_add_f32 v[16:17], v[36:37], v[38:39]
	v_pk_add_f32 v[32:33], v[40:41], v[42:43]
	v_mov_b32_e32 v25, v22
	v_pk_add_f32 v[16:17], v[16:17], v[32:33]
	v_mov_b32_e32 v32, v29
	v_mov_b32_e32 v33, v30
	v_mov_b32_e32 v29, v31
	v_pk_add_f32 v[28:29], v[32:33], v[28:29]
	v_pk_add_f32 v[16:17], v[16:17], v[16:17] op_sel:[0,1] op_sel_hi:[1,0]
	v_pk_add_f32 v[28:29], v[28:29], v[28:29] op_sel:[0,1] op_sel_hi:[1,0]
	v_mov_b32_e32 v17, v20
	v_mov_b32_e32 v29, v21
	v_mov_b32_e32 v27, v23
	v_pk_add_f32 v[16:17], v[16:17], v[28:29]
	v_pk_add_f32 v[20:21], v[24:25], v[26:27]
	s_nop 0
	v_pk_add_f32 v[16:17], v[16:17], v[20:21]
	s_nop 0
	v_add_f32_e32 v1, v16, v17
	v_fmamk_f32 v1, v1, 0x3a000000, v222
	v_cmp_gt_f32_e32 vcc, s33, v1
	v_mul_f32_e32 v7, 0x4b800000, v1
	s_nop 0
	v_cndmask_b32_e32 v1, v1, v7, vcc
	v_rsq_f32_e32 v1, v1
	s_nop 0
	v_mul_f32_e32 v7, 0x45800000, v1
	v_cndmask_b32_e32 v1, v1, v7, vcc
	v_mul_f32_e32 v1, v2, v1
	v_cvt_pk_bf16_f32 v2, v1, s0
	v_mad_i64_i32 v[0:1], s[4:5], v0, s96, v[12:13]
	v_lshl_add_u64 v[0:1], v[0:1], 0, v[10:11]
	v_lshl_add_u64 v[0:1], v[0:1], 0, v[176:177]
	v_add_co_u32_e32 v0, vcc, s31, v0
	s_nop 1
	v_addc_co_u32_e32 v1, vcc, 0, v1, vcc
	global_store_short v[0:1], v2, off offset:2048
	v_or_b32_e32 v0, 3, v14
	v_ashrrev_i32_e32 v1, 31, v0
	v_lshlrev_b64 v[14:15], 7, v[0:1]
	v_lshl_add_u64 v[14:15], s[8:9], 0, v[14:15]
	global_load_dwordx4 v[20:23], v[14:15], off offset:48
	global_load_dwordx4 v[24:27], v[14:15], off offset:32
	global_load_dwordx4 v[28:31], v[14:15], off
	global_load_dwordx4 v[32:35], v[14:15], off offset:16
	s_waitcnt vmcnt(3)
	v_add_f32_e32 v36, v20, v21
	v_add_f32_e32 v38, v22, v23
	s_waitcnt vmcnt(1)
	v_mov_b32_e32 v16, v28
	s_waitcnt vmcnt(0)
	v_mov_b32_e32 v17, v32
	v_mov_b32_e32 v32, v29
	v_mov_b32_e32 v28, v30
	v_mov_b32_e32 v29, v34
	v_mov_b32_e32 v34, v31
	v_pk_add_f32 v[16:17], v[16:17], v[32:33]
	v_pk_add_f32 v[28:29], v[28:29], v[34:35]
	s_nop 0
	v_pk_add_f32 v[16:17], v[16:17], v[28:29]
	s_nop 0
	v_add_f32_e32 v1, 0, v16
	v_add_f32_e32 v32, v1, v17
	v_mov_b32_e32 v16, v25
	v_mov_b32_e32 v17, v26
	v_mov_b32_e32 v25, v27
	v_pk_add_f32 v[16:17], v[16:17], v[24:25]
	s_nop 0
	v_pk_add_f32 v[34:35], v[16:17], v[16:17] op_sel:[0,1] op_sel_hi:[1,0]
	global_load_dwordx4 v[20:23], v[14:15], off offset:112
	global_load_dwordx4 v[24:27], v[14:15], off offset:96
	global_load_dwordx4 v[28:31], v[14:15], off offset:80
	s_nop 0
	global_load_dwordx4 v[14:17], v[14:15], off offset:64
	s_waitcnt vmcnt(2)
	v_add_f32_e32 v24, v24, v25
	v_add_f32_e32 v26, v26, v27
	s_waitcnt vmcnt(0)
	v_mov_b32_e32 v33, v14
	v_mov_b32_e32 v35, v15
	v_mov_b32_e32 v37, v16
	v_mov_b32_e32 v39, v17
	v_pk_add_f32 v[14:15], v[32:33], v[34:35]
	v_pk_add_f32 v[16:17], v[36:37], v[38:39]
	v_mov_b32_e32 v25, v22
	v_pk_add_f32 v[14:15], v[14:15], v[16:17]
	v_mov_b32_e32 v16, v29
	v_mov_b32_e32 v17, v30
	v_mov_b32_e32 v29, v31
	v_pk_add_f32 v[16:17], v[16:17], v[28:29]
	v_pk_add_f32 v[14:15], v[14:15], v[14:15] op_sel:[0,1] op_sel_hi:[1,0]
	v_pk_add_f32 v[16:17], v[16:17], v[16:17] op_sel:[0,1] op_sel_hi:[1,0]
	v_mov_b32_e32 v15, v20
	v_mov_b32_e32 v17, v21
	v_mov_b32_e32 v27, v23
	v_pk_add_f32 v[14:15], v[14:15], v[16:17]
	v_pk_add_f32 v[16:17], v[24:25], v[26:27]
	s_nop 0
	v_pk_add_f32 v[14:15], v[14:15], v[16:17]
	s_nop 0
	v_add_f32_e32 v1, v14, v15
	v_fmamk_f32 v1, v1, 0x3a000000, v222
	v_cmp_gt_f32_e32 vcc, s33, v1
	v_mul_f32_e32 v2, 0x4b800000, v1
	s_nop 0
	v_cndmask_b32_e32 v1, v1, v2, vcc
	v_rsq_f32_e32 v1, v1
	s_nop 0
	v_mul_f32_e32 v2, 0x45800000, v1
	v_cndmask_b32_e32 v1, v1, v2, vcc
	v_mul_f32_e32 v1, v3, v1
	v_cvt_pk_bf16_f32 v2, v1, s0
	v_mad_i64_i32 v[0:1], s[4:5], v0, s96, v[12:13]
	v_lshl_add_u64 v[0:1], v[0:1], 0, v[10:11]
	v_lshl_add_u64 v[0:1], v[0:1], 0, v[176:177]
	v_add_co_u32_e32 v0, vcc, 0x2000, v0
	s_nop 1
	v_addc_co_u32_e32 v1, vcc, 0, v1, vcc
	global_store_short v[0:1], v2, off offset:2048
	s_cbranch_scc0 .LBB0_511
